# LEADER-LEAN: waiting XCD leaders invalidate when they start waiting and skip the post-release invalidate and acknowledge wait (on REL-FIRST)
# baseline (speedup 1.0000x reference)
.LBB0_93:
	s_or_b64 exec, exec, s[12:13]
	s_cmp_eq_u32 s97, 1
	s_cbranch_scc1 .Llean_11
	buffer_inv sc1
	s_waitcnt vmcnt(0)
.Llean_11:
.LBB0_94:
	s_or_b64 exec, exec, s[6:7]
	s_waitcnt lgkmcnt(0)
	s_barrier

.Llean_7:
.LBB0_570:
	s_or_b64 exec, exec, s[4:5]
	s_waitcnt lgkmcnt(0)
	s_barrier
